# attention K/V staging via LDS-DMA (global_load_lds_dwordx4) into an unpadded XOR-swizzled LDS image; register staging and ds_write_b128 removed
# speedup vs baseline: 1.0112x; 1.0112x over previous
; __device__ __forceinline__ void phase_attn(KP P, int l_, unsigned char* shm) {
;     ...
;     const float lam_init = 0.8f - 0.6f * __expf(-0.3f * (float)l);
;     float lam;
;     { const float* lq = P->in[11] + (size_t)l * 256; const float s1 = wave_sum(lq[lane] * lq[64 + lane]), s2 = wave_sum(lq[128 + lane] * lq[192 + lane]); lam = __expf(s1) - __expf(s2) + lam_init; }
.LBB0_2646:
	s_or_b64 exec, exec, s[4:5]
	v_readlane_b32 s0, v255, 1
	s_mov_b64 s[42:43], s[72:73]
	s_mov_b32 s8, s0
	s_waitcnt lgkmcnt(0)
	v_mov_b32_e32 v0, v228
	s_barrier
	s_load_dwordx2 s[4:5], s[42:43], 0x58
	s_ashr_i32 s9, s8, 31
	s_lshl_b64 s[6:7], s[8:9], 10
	v_and_b32_e32 v2, 63, v0
	v_lshlrev_b32_e32 v1, 2, v2
	s_waitcnt lgkmcnt(0)
	s_add_u32 s6, s4, s6
	s_addc_u32 s7, s5, s7
	global_load_dword v3, v1, s[6:7]
	global_load_dword v4, v1, s[6:7] offset:256
	v_readlane_b32 s0, v254, 6
	v_readlane_b32 s1, v254, 7
	s_and_b64 vcc, exec, s[0:1]
	s_waitcnt vmcnt(0)
	v_mul_f32_e32 v6, v3, v4
	s_nop 1
	v_mov_b32_dpp v6, v6 quad_perm:[1,0,3,2] row_mask:0xf bank_mask:0xf bound_ctrl:1
	v_fmac_f32_e32 v6, v3, v4
	v_mov_b32_e32 v4, v5
	s_nop 0
	v_add_f32_dpp v3, v6, v6 quad_perm:[2,3,0,1] row_mask:0xf bank_mask:0xf bound_ctrl:1
	s_nop 1
	v_add_f32_dpp v3, v3, v3 row_half_mirror row_mask:0xf bank_mask:0xf bound_ctrl:1
	s_nop 1
	v_add_f32_dpp v3, v3, v3 row_mirror row_mask:0xf bank_mask:0xf bound_ctrl:1
	s_nop 1
	v_mov_b32_dpp v4, v3 row_bcast:15 row_mask:0xa bank_mask:0xf
	v_add_f32_e32 v3, v3, v4
	v_mov_b32_e32 v4, v5
	s_nop 1
	v_mov_b32_dpp v4, v3 row_bcast:31 row_mask:0xc bank_mask:0xf
	v_add_f32_e32 v3, v3, v4
	s_nop 0
	v_readlane_b32 s4, v3, 63
	global_load_dword v3, v1, s[6:7] offset:512
	global_load_dword v4, v1, s[6:7] offset:768
	s_waitcnt vmcnt(0)
	v_mul_f32_e32 v6, v3, v4
	s_nop 1
	v_mov_b32_dpp v6, v6 quad_perm:[1,0,3,2] row_mask:0xf bank_mask:0xf bound_ctrl:1
	v_fmac_f32_e32 v6, v3, v4
	v_mov_b32_e32 v4, v5
	s_nop 0
	v_add_f32_dpp v3, v6, v6 quad_perm:[2,3,0,1] row_mask:0xf bank_mask:0xf bound_ctrl:1
	s_nop 1
	v_add_f32_dpp v3, v3, v3 row_half_mirror row_mask:0xf bank_mask:0xf bound_ctrl:1
	s_nop 1
	v_add_f32_dpp v3, v3, v3 row_mirror row_mask:0xf bank_mask:0xf bound_ctrl:1
	s_nop 1
	v_mov_b32_dpp v4, v3 row_bcast:15 row_mask:0xa bank_mask:0xf
	v_add_f32_e32 v3, v3, v4
	v_mov_b32_e32 v4, v5
	s_nop 1
	v_mov_b32_dpp v4, v3 row_bcast:31 row_mask:0xc bank_mask:0xf
	v_add_f32_e32 v3, v3, v4
	s_nop 0
	v_readlane_b32 s5, v3, 63
	s_cbranch_vccz .LBB0_2668
; __device__ __forceinline__ void phase_attn(KP P, int l_, unsigned char* shm) {
;     ...
;     const int tid = ltid(), wave = tid >> 6, lane = tid & 63, mp = wave >> 2, rq = wave & 3, l15 = lane & 15, g = lane >> 4;
;     const u16* pA = (const u16*)(P->ws + WS_P);
;     u16* OA = (u16*)(P->ws + WS_O);
;     constexpr int KROW = 72, VROW = 136, KT_B = 128 * KROW * 2, VT_B = 128 * VROW * 2, STG = 2 * KT_B + VT_B;
;     const u16* vTg = (const u16*)(P->ws + WS_LO);
;     const float lam_init = 0.8f - 0.6f * __expf(-0.3f * (float)l);
;     float lam;
;     { const float* lq = P->in[11] + (size_t)l * 256; const float s1 = wave_sum(lq[lane] * lq[64 + lane]), s2 = wave_sum(lq[128 + lane] * lq[192 + lane]); lam = __expf(s1) - __expf(s2) + lam_init; }
;     for (int it = blockIdx.x; it < 4096; it += gridDim.x) {
;         const int j = it & 255, pi = 15 - (it >> 8), bh = j >> 1, half = j & 1, b = bh >> 2, h = bh & 3;
;         const int qb = (pi >> 1) * 4 + ((pi & 1) ? (half ? 2 : 3) : (half ? 1 : 0));
;         const int q0 = qb * 64, nt = (qb >> 1) + 1;
;         const size_t tok0 = (size_t)b * SEQ;
;         bf16x8 qf[2];
;         { const u16* qp = pA + (tok0 + q0 + rq * 16 + l15) * 1536 + h * 128 + mp * 64 + g * 8;
;           qf[0] = *(const bf16x8*)qp; qf[1] = *(const bf16x8*)(qp + 32); }
;         f32x4 ot[8];
; #pragma unroll
;         for (int e = 0; e < 8; ++e) ot[e] = (f32x4){0.f, 0.f, 0.f, 0.f};
;         float mrun = -INFINITY, lrun = 0.f;
;         uint4 kreg0, kreg1, kreg2, kreg3, vreg0, vreg1, vreg2, vreg3;
;         const int kc_key = (tid >> 3) & 63, kc_ch = tid & 7, vc_e = tid >> 4, vc_ch = tid & 15;
;         const u16* kgb = pA + (tok0 + kc_key) * 1536 + 512 + h * 128 + kc_ch * 8;
;         const u16* vTb = vTg + ((size_t)bh * 128 + vc_e) * SEQ + vc_ch * 8;
;     ...
;         ATT_GLOAD(0); ATT_LSTORE(0); __syncthreads();
;         for (int t = 0; t < nt; ++t) {
;             if (t + 1 < nt) ATT_GLOAD(t + 1);
;             const unsigned char* base = shm + (t & 1) * STG;
; #pragma unroll
;             for (int hf = 0; hf < 2; ++hf) {
;                 const int kb = 2 * t + hf;
;                 if (kb <= qb) {
;                     const u16* Ks = (const u16*)(base + mp * KT_B) + hf * 64 * KROW;
;                     const u16* Vt = (const u16*)(base + 2 * KT_B) + hf * 64;
;                     f32x4 st[4];
;                     bf16x8 kfr[4][2];
	v_cvt_f32_i32_e32 v3, s8
	v_mov_b32_e32 v6, 0x3fb8aa3b
	v_mul_f32_e32 v4, s4, v6
	v_mul_f32_e32 v6, s5, v6
	v_mul_f32_e32 v3, 0xbe99999a, v3
	v_mul_f32_e32 v3, 0x3fb8aa3b, v3
	v_exp_f32_e32 v3, v3
	v_exp_f32_e32 v4, v4
	v_exp_f32_e32 v6, v6
	v_mov_b32_e32 v7, 0x3f4ccccd
	v_fmamk_f32 v3, v3, 0xbf19999a, v7
	v_lshrrev_b32_e32 v8, 4, v2
	v_sub_f32_e32 v4, v4, v6
	v_add_f32_e32 v165, v3, v4
	v_and_b32_e32 v4, 15, v0
	v_bfe_u32 v10, v0, 6, 2
	v_lshlrev_b32_e32 v164, 2, v8
	v_lshl_or_b32 v194, v10, 4, v4
	v_sub_f32_e32 v197, 1.0, v3
	v_or_b32_e32 v3, 2, v164
	v_cmp_gt_u32_e64 s[12:13], v3, v194
	v_or_b32_e32 v3, 3, v164
	v_cmp_gt_u32_e64 s[14:15], v3, v194
	v_or_b32_e32 v3, 16, v164
	v_cmp_gt_u32_e64 s[16:17], v3, v194
	v_or_b32_e32 v3, 17, v164
	v_cmp_gt_u32_e64 s[18:19], v3, v194
	v_or_b32_e32 v3, 18, v164
	s_load_dwordx2 s[48:49], s[42:43], 0xf8
	v_cmp_gt_u32_e64 s[20:21], v3, v194
	v_or_b32_e32 v3, 19, v164
	v_cmp_gt_u32_e64 s[22:23], v3, v194
	v_or_b32_e32 v3, 32, v164
	v_lshlrev_b32_e32 v6, 3, v0
	v_cmp_gt_u32_e64 s[24:25], v3, v194
	v_or_b32_e32 v3, 33, v164
	v_and_b32_e32 v2, 56, v6
	v_and_b32_e32 v6, 0x78, v6
	v_cmp_gt_u32_e64 s[26:27], v3, v194
	v_or_b32_e32 v3, 34, v164
	v_lshlrev_b32_e32 v160, 1, v6
	v_mov_b32_e32 v161, v5
	v_cmp_gt_u32_e64 s[28:29], v3, v194
	v_or_b32_e32 v3, 35, v164
	v_bfe_u32 v169, v0, 3, 6
	s_waitcnt lgkmcnt(0)
	v_lshl_add_u64 v[6:7], s[48:49], 0, v[160:161]
	s_mov_b64 s[0:1], 0x2bb00000
	v_cmp_gt_u32_e64 s[30:31], v3, v194
	v_or_b32_e32 v3, 48, v164
	v_lshl_add_u64 v[162:163], v[6:7], 0, s[0:1]
	v_mul_u32_u24_e32 v6, 0x48, v169
	v_cmp_gt_u32_e64 s[34:35], v3, v194
	v_or_b32_e32 v3, 49, v164
	s_add_u32 s50, s48, 0x17b00000
	v_ashrrev_i32_e32 v158, 4, v0
	v_lshlrev_b32_e32 v161, 1, v6
	v_lshlrev_b32_e32 v6, 1, v2
	s_movk_i32 s0, 0x88
	v_cmp_gt_u32_e64 s[36:37], v3, v194
	v_or_b32_e32 v3, 50, v164
	s_addc_u32 s51, s49, 0
	v_lshrrev_b32_e32 v9, 6, v0
	v_ashrrev_i32_e32 v11, 8, v0
	v_ashrrev_i32_e32 v159, 31, v158
	v_add3_u32 v190, 0, v161, v6
	v_mul_lo_u32 v6, v158, s0
	v_xor_b32_e32 v195, 64, v1
	v_xor_b32_e32 v196, 0x80, v1
	v_lshl_add_u32 v1, v4, 2, 0
	s_movk_i32 s0, 0x100
	v_cmp_gt_u32_e64 s[38:39], v3, v194
	v_or_b32_e32 v3, 51, v164
	s_add_u32 s60, s48, 0x27b00000
	v_lshlrev_b32_e32 v154, 6, v11
	v_lshlrev_b32_e32 v156, 3, v8
	v_lshlrev_b32_e32 v191, 1, v6
	v_cmp_gt_u32_e64 s[6:7], s0, v0
	v_cmp_gt_u32_e64 s[40:41], v3, v194
	v_lshlrev_b32_e32 v3, 8, v8
	v_lshl_add_u32 v6, v10, 13, v1
	v_lshl_add_u32 v1, v9, 13, v1
	v_lshlrev_b64 v[166:167], 12, v[158:159]
	v_and_b32_e32 v0, 7, v0
	s_addc_u32 s61, s49, 0
	v_ashrrev_i32_e32 v155, 31, v154
	v_add3_u32 v192, 0, v191, v160
	v_mul_i32_i24_e32 v193, 0x4800, v11
	v_cmp_eq_u32_e64 s[4:5], 1, v11
	s_lshl_b64 s[54:55], s[8:9], 9
	v_mul_u32_u24_e32 v198, 0x90, v4
	v_mul_u32_u24_e32 v199, 0x110, v4
	v_cmp_gt_u32_e64 s[8:9], v164, v194
	v_cmp_lt_u32_e64 s[10:11], v164, v194
	v_lshl_or_b32 v166, v4, 4, v166
	v_lshlrev_b32_e32 v168, 4, v0
	v_mov_b32_e32 v157, v5
	v_lshlrev_b32_e32 v170, 1, v156
	v_lshlrev_b32_e32 v172, 1, v2
	v_add_u32_e32 v200, v6, v3
	v_add_u32_e32 v201, v1, v3
	v_bfe_u32 v0, v228, 3, 6
	v_bfe_u32 v1, v0, 1, 3
	v_and_b32_e32 v2, 7, v228
	v_xor_b32_e32 v1, v1, v2
	v_lshlrev_b32_e32 v1, 4, v1
	v_lshl_add_u32 v190, v0, 7, v1
	v_lshrrev_b32_e32 v0, 4, v228
	v_and_b32_e32 v1, 15, v0
	v_add_u32_e32 v2, 4, v1
	v_bfe_u32 v2, v2, 3, 1
	v_xor_b32_e32 v1, v1, v2
	v_and_b32_e32 v2, 15, v228
	v_xor_b32_e32 v1, v1, v2
	v_lshlrev_b32_e32 v1, 4, v1
	v_lshl_add_u32 v192, v0, 8, v1
	v_add_u32_e32 v192, 0x8000, v192
	v_and_b32_e32 v0, 15, v228
	v_bfe_u32 v1, v228, 4, 2
	v_lshrrev_b32_e32 v2, 1, v0
	v_xor_b32_e32 v2, v2, v1
	v_lshlrev_b32_e32 v3, 7, v0
	v_lshl_add_u32 v198, v2, 4, v3
	v_xor_b32_e32 v2, 4, v2
	v_lshl_add_u32 v199, v2, 4, v3
	v_lshrrev_b32_e32 v2, 8, v228
	v_lshlrev_b32_e32 v2, 14, v2
	v_add_u32_e32 v198, v198, v2
	v_add_u32_e32 v199, v199, v2
	v_add_u32_e32 v2, 4, v0
	v_bfe_u32 v2, v2, 3, 1
	v_xor_b32_e32 v2, v2, v0
	v_lshlrev_b32_e32 v3, 8, v0
	v_add_u32_e32 v3, 0x8000, v3
	v_xor_b32_e32 v1, v1, v2
	v_lshl_add_u32 v161, v1, 4, v3
	v_xor_b32_e32 v2, 4, v1
	v_lshl_add_u32 v191, v2, 4, v3
	v_xor_b32_e32 v2, 8, v1
	v_lshl_add_u32 v160, v2, 4, v3
	v_xor_b32_e32 v2, 12, v1
	v_lshl_add_u32 v210, v2, 4, v3
	v_lshrrev_b32_e32 v0, 6, v228
	v_and_b32_e32 v1, 63, v228
	s_nop 0
	v_readfirstlane_b32 s32, v0
	s_lshl_b32 s32, s32, 12
	v_and_b32_e32 v2, 3, v0
	v_lshrrev_b32_e32 v3, 3, v1
	v_lshl_add_u32 v2, v2, 5, v3
	v_mul_u32_u24_e32 v2, 0xc00, v2
	v_lshrrev_b32_e32 v6, 2, v0
	v_lshl_add_u32 v2, v6, 7, v2
	v_and_b32_e32 v6, 7, v1
	v_lshrrev_b32_e32 v7, 1, v3
	v_xor_b32_e32 v6, v6, v7
	v_xor_b32_e32 v7, 4, v6
	v_lshl_add_u32 v202, v6, 4, v2
	v_lshl_add_u32 v203, v7, 4, v2
	v_add_u32_e32 v203, 0x6000, v203
	v_lshl_add_u32 v211, v6, 4, v2
	v_add_u32_e32 v211, 0xc000, v211
	v_lshl_add_u32 v235, v7, 4, v2
	v_add_u32_e32 v235, 0x12000, v235
	v_lshrrev_b32_e32 v3, 4, v1
	v_and_b32_e32 v6, 15, v1
	v_lshl_add_u32 v2, v0, 4, v3
	v_lshlrev_b32_e32 v2, 12, v2
	v_mov_b32_e32 v7, v3
	v_add_u32_e32 v8, 4, v7
	v_bfe_u32 v8, v8, 3, 1
	v_xor_b32_e32 v7, v7, v8
	v_xor_b32_e32 v7, v7, v6
	v_lshl_add_u32 v239, v7, 4, v2
	v_add_u32_e32 v7, 4, v3
	v_add_u32_e32 v8, 4, v7
	v_bfe_u32 v8, v8, 3, 1
	v_xor_b32_e32 v7, v7, v8
	v_xor_b32_e32 v7, v7, v6
	v_lshl_add_u32 v240, v7, 4, v2
	v_add_u32_e32 v240, 0x4000, v240
	v_add_u32_e32 v7, 8, v3
	v_add_u32_e32 v8, 4, v7
	v_bfe_u32 v8, v8, 3, 1
	v_xor_b32_e32 v7, v7, v8
	v_xor_b32_e32 v7, v7, v6
	v_lshl_add_u32 v247, v7, 4, v2
	v_add_u32_e32 v247, 0x8000, v247
	v_add_u32_e32 v7, 12, v3
	v_add_u32_e32 v8, 4, v7
	v_bfe_u32 v8, v8, 3, 1
	v_xor_b32_e32 v7, v7, v8
	v_xor_b32_e32 v7, v7, v6
	v_lshl_add_u32 v193, v7, 4, v2
	v_add_u32_e32 v193, 0xc000, v193
	s_mov_b32 s62, s2
	s_branch .LBB0_2649

; __device__ __forceinline__ void phase_attn(KP P, int l_, unsigned char* shm) {
;     ...
;     for (int it = blockIdx.x; it < 4096; it += gridDim.x) {
;         const int j = it & 255, pi = 15 - (it >> 8), bh = j >> 1, half = j & 1, b = bh >> 2, h = bh & 3;
;         const int qb = (pi >> 1) * 4 + ((pi & 1) ? (half ? 2 : 3) : (half ? 1 : 0));
;         const int q0 = qb * 64, nt = (qb >> 1) + 1;
;         const size_t tok0 = (size_t)b * SEQ;
;         bf16x8 qf[2];
;         { const u16* qp = pA + (tok0 + q0 + rq * 16 + l15) * 1536 + h * 128 + mp * 64 + g * 8;
;           qf[0] = *(const bf16x8*)qp; qf[1] = *(const bf16x8*)(qp + 32); }
;         f32x4 ot[8];
; #pragma unroll
;         for (int e = 0; e < 8; ++e) ot[e] = (f32x4){0.f, 0.f, 0.f, 0.f};
;         float mrun = -INFINITY, lrun = 0.f;
;         uint4 kreg0, kreg1, kreg2, kreg3, vreg0, vreg1, vreg2, vreg3;
;         const int kc_key = (tid >> 3) & 63, kc_ch = tid & 7, vc_e = tid >> 4, vc_ch = tid & 15;
;         const u16* kgb = pA + (tok0 + kc_key) * 1536 + 512 + h * 128 + kc_ch * 8;
;         const u16* vTb = vTg + ((size_t)bh * 128 + vc_e) * SEQ + vc_ch * 8;
;     ...
;         ATT_GLOAD(0); ATT_LSTORE(0); __syncthreads();
;         for (int t = 0; t < nt; ++t) {
;             if (t + 1 < nt) ATT_GLOAD(t + 1);
;             const unsigned char* base = shm + (t & 1) * STG;
; #pragma unroll
;             for (int hf = 0; hf < 2; ++hf) {
;                 const int kb = 2 * t + hf;
;                 if (kb <= qb) {
;                     const u16* Ks = (const u16*)(base + mp * KT_B) + hf * 64 * KROW;
;                     const u16* Vt = (const u16*)(base + 2 * KT_B) + hf * 64;
.LBB0_2649:
	s_lshr_b32 s0, s62, 8
	s_and_b32 s1, s62, 7
	s_lshl_b32 s1, s1, 4
	s_or_b32 s1, s1, s0
	s_bfe_u32 s52, s62, 0x50003
	s_and_b32 s56, s0, 30
	s_add_i32 s52, s52, s56
	s_and_b32 s52, s52, 31
	s_sub_i32 s56, 31, s52
	s_bitcmp1_b32 s0, 0
	s_cselect_b32 s52, s56, s52
	s_lshr_b32 s56, s52, 1
	s_xor_b32 s57, s52, s56
	s_and_b32 s57, s57, 1
	s_sub_i32 s56, 15, s56
	s_lshl_b32 s56, s56, 8
	s_lshl_b32 s1, s1, 1
	s_or_b32 s98, s56, s1
	s_or_b32 s98, s98, s57
	s_bfe_u32 s0, s98, 0x70001
	s_lshl_b32 s52, s0, 19
	v_lshl_add_u64 v[174:175], v[166:167], 0, s[52:53]
	s_ashr_i32 s52, s98, 8
	s_sub_i32 s52, 15, s52
	s_lshl_b32 s1, s98, 7
	s_and_b32 s56, s98, 1
	s_lshl_b32 s57, s52, 1
	s_and_b32 s1, s1, 0x300
	s_and_b32 s57, s57, 0x7ffffffc
	s_and_b32 s52, s52, 1
	s_xor_b32 s58, s56, 3
	s_cmp_eq_u32 s52, 0
	s_cselect_b32 s52, s56, s58
	s_or_b32 s58, s52, s57
	s_lshl_b32 s56, s98, 8
	s_lshl_b32 s52, s58, 6
	s_and_b32 s59, s56, 0xf800
	s_add_i32 s52, s52, s59
	v_or_b32_e32 v4, s52, v194
	s_lshl_b32 s52, s98, 6
	v_mov_b64_e32 v[0:1], s[50:51]
	s_and_b32 s63, s52, 0x180
	v_mad_u64_u32 v[0:1], s[56:57], v4, s83, v[0:1]
	s_lshl_b32 s52, s63, 1
	s_mul_i32 s64, s59, 0xc00
	s_add_i32 s64, s64, s1
	s_add_u32 s98, s50, s64
	s_addc_u32 s99, s51, 0
	s_add_u32 s98, s98, 0x400
	s_addc_u32 s99, s99, 0
	s_lshl_b32 s64, s0, 19
	s_add_u32 s100, s48, s64
	s_addc_u32 s101, s49, 0
	s_add_u32 s100, s100, 0x2bb00000
	s_addc_u32 s101, s101, 0
	s_waitcnt vmcnt(1)
	v_lshl_add_u64 v[18:19], v[0:1], 0, s[52:53]
	v_or_b32_e32 v0, s59, v169
	v_mul_u32_u24_e32 v0, 0x600, v0
	v_lshlrev_b32_e32 v50, 1, v0
	v_mov_b32_e32 v51, v5
	v_lshl_add_u64 v[0:1], s[50:51], 0, v[50:51]
	v_lshl_add_u64 v[0:1], v[0:1], 0, s[52:53]
	v_mov_b32_e32 v173, v5
	s_lshl_b32 s52, s0, 7
	v_lshl_add_u64 v[6:7], v[0:1], 0, v[172:173]
	v_lshl_add_u64 v[0:1], s[52:53], 0, v[158:159]
	s_mov_b32 s0, 0x30000
	v_lshlrev_b64 v[0:1], 12, v[0:1]
	v_add_co_u32_e32 v14, vcc, s0, v6
	v_lshl_add_u64 v[20:21], v[162:163], 0, v[0:1]
	s_nop 0
	v_addc_co_u32_e32 v15, vcc, 0, v7, vcc
	s_mov_b32 s0, 0x20000
	s_waitcnt vmcnt(0)
	v_add_co_u32_e32 v22, vcc, s0, v20
	s_mov_b32 m0, s32
	s_nop 0
	global_load_lds_dwordx4 v202, s[98:99]
	s_add_i32 m0, s32, 0x400
	s_nop 0
	global_load_lds_dwordx4 v203, s[98:99]
	s_add_i32 m0, s32, 0x800
	s_nop 0
	global_load_lds_dwordx4 v211, s[98:99]
	s_add_i32 m0, s32, 0xc00
	s_nop 0
	global_load_lds_dwordx4 v235, s[98:99]
	s_add_i32 m0, s32, 0x8000
	s_nop 0
	global_load_lds_dwordx4 v239, s[100:101]
	s_add_i32 m0, s32, 0x8400
	s_nop 0
	global_load_lds_dwordx4 v240, s[100:101]
	s_add_i32 m0, s32, 0x8800
	s_nop 0
	global_load_lds_dwordx4 v247, s[100:101]
	s_add_i32 m0, s32, 0x8c00
	s_nop 0
	global_load_lds_dwordx4 v193, s[100:101]
	s_nop 0
	s_nop 0
	v_addc_co_u32_e32 v23, vcc, 0, v21, vcc
	s_nop 0
	v_add_co_u32_e32 v22, vcc, s85, v20
	s_mov_b32 s0, 0x60000
	s_nop 0
	v_addc_co_u32_e32 v23, vcc, 0, v21, vcc
	v_add_co_u32_e32 v20, vcc, s0, v20
	v_lshl_add_u64 v[18:19], v[154:155], 1, v[18:19]
	v_mov_b32_e32 v171, v5
	v_addc_co_u32_e32 v21, vcc, 0, v21, vcc
	v_lshl_add_u64 v[22:23], v[18:19], 0, v[170:171]
	global_load_dwordx4 v[18:21], v[22:23], off
	s_nop 0
	global_load_dwordx4 v[22:25], v[22:23], off offset:64
	v_mov_b32_e32 v70, v5
	v_mov_b32_e32 v71, v5
	v_mov_b32_e32 v72, v5
	v_mov_b32_e32 v73, v5
	v_mov_b64_e32 v[66:67], v[70:71]
	v_mov_b64_e32 v[62:63], v[70:71]
	v_mov_b64_e32 v[54:55], v[70:71]
	v_mov_b64_e32 v[46:47], v[70:71]
	v_mov_b64_e32 v[42:43], v[70:71]
	s_and_b32 s65, s58, 0x7ffffffe
	v_or3_b32 v176, v168, s1, v50
	v_mov_b64_e32 v[50:51], v[70:71]
	v_mov_b64_e32 v[58:59], v[70:71]
	s_mov_b32 s52, 0
	v_mov_b32_e32 v177, v157
	v_mov_b32_e32 v171, 0
	v_mov_b32_e32 v248, 0
	v_mov_b32_e32 v249, 0
	v_mov_b32_e32 v250, 0
	v_mov_b32_e32 v251, 0
	v_mov_b32_e32 v252, 0xff800000
	v_mov_b32_e32 v253, 0xff800000
	v_mov_b64_e32 v[68:69], v[72:73]
	v_mov_b64_e32 v[64:65], v[72:73]
	v_mov_b64_e32 v[56:57], v[72:73]
	v_mov_b64_e32 v[48:49], v[72:73]
	v_mov_b64_e32 v[44:45], v[72:73]
	s_lshr_b32 s59, s58, 1
	s_add_i32 s64, s58, -1
	s_add_i32 s65, s65, 2
	v_mov_b64_e32 v[52:53], v[72:73]
	v_mov_b64_e32 v[60:61], v[72:73]
	s_mov_b32 s70, 0
	s_waitcnt vmcnt(0) lgkmcnt(0)
	s_barrier
	s_branch .LBB0_2651
.LBB0_2650:
	s_mov_b64 s[56:57], 0x100
	s_add_i32 s52, s52, 2
	v_lshl_add_u64 v[174:175], v[174:175], 0, s[56:57]
	s_mov_b64 s[56:57], 0x60000
	s_cmp_eq_u32 s65, s52
	v_lshl_add_u64 v[176:177], v[176:177], 0, s[56:57]
	s_waitcnt vmcnt(0) lgkmcnt(0)
	s_barrier
	s_cbranch_scc1 .LBB0_2663
.LBB0_2651:
	s_cmp_lt_u32 s70, s59
	s_cselect_b64 s[56:57], -1, 0
	s_cmp_ge_u32 s70, s59
	s_cbranch_scc1 .LBB0_2653
	s_add_u32 s98, s98, 0x60000
	s_addc_u32 s99, s99, 0
	s_add_u32 s100, s100, 0x100
	s_addc_u32 s101, s101, 0
	s_bitcmp0_b32 s70, 0
	s_cselect_b32 s1, 0x10000, 0
	s_add_i32 s1, s1, s32
	s_mov_b32 m0, s1
	s_nop 0
	global_load_lds_dwordx4 v202, s[98:99]
	s_add_i32 m0, s1, 0x400
	s_nop 0
	global_load_lds_dwordx4 v203, s[98:99]
	s_add_i32 m0, s1, 0x800
	s_nop 0
	global_load_lds_dwordx4 v211, s[98:99]
	s_add_i32 m0, s1, 0xc00
	s_nop 0
	global_load_lds_dwordx4 v235, s[98:99]
	s_add_i32 m0, s1, 0x8000
	s_nop 0
	global_load_lds_dwordx4 v239, s[100:101]
	s_add_i32 m0, s1, 0x8400
	s_nop 0
	global_load_lds_dwordx4 v240, s[100:101]
	s_add_i32 m0, s1, 0x8800
	s_nop 0
	global_load_lds_dwordx4 v247, s[100:101]
	s_add_i32 m0, s1, 0x8c00
	s_nop 0
	global_load_lds_dwordx4 v193, s[100:101]
.LBB0_2653:
	s_bitcmp1_b32 s70, 0
	s_cselect_b32 s0, 0x10000, 0
	v_add_u32_e32 v208, s0, v198
	v_add_u32_e32 v209, s0, v199
	s_cmp_gt_u32 s52, s58
	v_add_u32_e32 v207, s0, v161
	v_add_u32_e32 v206, s0, v191
	v_add_u32_e32 v205, s0, v160
	v_add_u32_e32 v204, s0, v210
	s_cbranch_scc0 .LBB0_2656
	s_cmp_ge_u32 s52, s58
	s_cbranch_scc0 .LBB0_2659

; __device__ __forceinline__ void phase_attn(KP P, int l_, unsigned char* shm) {
;     ...
;                     const u16* Ks = (const u16*)(base + mp * KT_B) + hf * 64 * KROW;
;                     const u16* Vt = (const u16*)(base + 2 * KT_B) + hf * 64;
;                     f32x4 st[4];
;                     bf16x8 kfr[4][2];
; #pragma unroll
;                     for (int kt = 0; kt < 4; ++kt)
; #pragma unroll
;                         for (int ks = 0; ks < 2; ++ks) kfr[kt][ks] = *(const bf16x8*)(Ks + (kt * 16 + l15) * KROW + ks * 32 + g * 8);
;                     uint2 vfa[8][2], vfb[8][2];
; #pragma unroll
;                     for (int e = 0; e < 8; ++e)
; #pragma unroll
;                         for (int k2 = 0; k2 < 2; ++k2) { const u16* vp = Vt + (e * 16 + l15) * VROW + k2 * 32 + g * 4; vfa[e][k2] = *(const uint2*)vp; vfb[e][k2] = *(const uint2*)(vp + 16); }
;                     __builtin_amdgcn_sched_barrier(0);
; #pragma unroll
;                     for (int kt = 0; kt < 4; ++kt) { st[kt] = (f32x4){0.f, 0.f, 0.f, 0.f};
; #pragma unroll
;                         for (int ks = 0; ks < 2; ++ks) st[kt] = __builtin_amdgcn_mfma_f32_16x16x32_bf16(kfr[kt][ks], qf[ks], st[kt], 0, 0, 0); }
;                     if (kb == qb) {
;                         asm volatile("" ::: "memory");
;                         const int qr = rq * 16 + l15;
; #pragma unroll
;                         for (int kt = 0; kt < 4; ++kt)
; #pragma unroll
;                             for (int jj = 0; jj < 4; ++jj) if (kt * 16 + g * 4 + jj > qr) st[kt][jj] = -INFINITY;
.LBB0_2656:
	ds_read_b128 v[138:141], v208
	ds_read_b128 v[142:145], v209
	ds_read_b128 v[146:149], v208 offset:2048
	ds_read_b128 v[212:215], v209 offset:2048
	ds_read_b128 v[216:219], v208 offset:4096
	ds_read_b128 v[220:223], v209 offset:4096
	ds_read_b128 v[224:227], v208 offset:6144
	ds_read_b128 v[242:245], v209 offset:6144
	ds_read_b128 v[134:137], v207
	ds_read_b128 v[130:133], v206
	ds_read_b128 v[126:129], v207 offset:4096
	ds_read_b128 v[122:125], v206 offset:4096
	ds_read_b128 v[118:121], v207 offset:8192
	ds_read_b128 v[114:117], v206 offset:8192
	ds_read_b128 v[110:113], v207 offset:12288
	ds_read_b128 v[106:109], v206 offset:12288
	ds_read_b128 v[102:105], v207 offset:16384
	ds_read_b128 v[98:101], v206 offset:16384
	ds_read_b128 v[94:97], v207 offset:20480
	ds_read_b128 v[90:93], v206 offset:20480
	ds_read_b128 v[86:89], v207 offset:24576
	ds_read_b128 v[82:85], v206 offset:24576
	ds_read_b128 v[78:81], v207 offset:28672
	ds_read_b128 v[74:77], v206 offset:28672
	s_waitcnt lgkmcnt(14)
	v_mfma_f32_16x16x32_bf16 v[138:141], v[138:141], v[18:21], v[248:251]
	s_cmp_lg_u32 s58, s52
	v_mfma_f32_16x16x32_bf16 v[150:153], v[142:145], v[22:25], v[138:141]
	v_mfma_f32_16x16x32_bf16 v[138:141], v[146:149], v[18:21], v[248:251]
	v_mfma_f32_16x16x32_bf16 v[146:149], v[212:215], v[22:25], v[138:141]
	v_mfma_f32_16x16x32_bf16 v[138:141], v[216:219], v[18:21], v[248:251]
	v_mfma_f32_16x16x32_bf16 v[142:145], v[224:227], v[18:21], v[248:251]
	v_mfma_f32_16x16x32_bf16 v[138:141], v[220:223], v[22:25], v[138:141]
	v_mfma_f32_16x16x32_bf16 v[142:145], v[242:245], v[22:25], v[142:145]
	s_cbranch_scc1 .LBB0_2658
	s_nop 0
	v_cndmask_b32_e64 v186, v150, v241, s[8:9]
	v_cndmask_b32_e64 v150, v186, v150, s[10:11]
	v_cndmask_b32_e64 v151, v241, v151, s[10:11]
	v_cndmask_b32_e64 v152, v152, v241, s[12:13]
	v_cndmask_b32_e64 v153, v153, v241, s[14:15]
	v_cndmask_b32_e64 v146, v146, v241, s[16:17]
	v_cndmask_b32_e64 v147, v147, v241, s[18:19]
	v_cndmask_b32_e64 v148, v148, v241, s[20:21]
	v_cndmask_b32_e64 v149, v149, v241, s[22:23]
	v_cndmask_b32_e64 v138, v138, v241, s[24:25]
	v_cndmask_b32_e64 v139, v139, v241, s[26:27]
	v_cndmask_b32_e64 v140, v140, v241, s[28:29]
	v_cndmask_b32_e64 v141, v141, v241, s[30:31]
	v_cndmask_b32_e64 v142, v142, v241, s[34:35]
	v_cndmask_b32_e64 v143, v143, v241, s[36:37]
	v_cndmask_b32_e64 v144, v144, v241, s[38:39]
	v_cndmask_b32_e64 v145, v145, v241, s[40:41]

; __device__ __forceinline__ void phase_attn(KP P, int l_, unsigned char* shm) {
;     ...
;                     const u16* Ks = (const u16*)(base + mp * KT_B) + hf * 64 * KROW;
;                     const u16* Vt = (const u16*)(base + 2 * KT_B) + hf * 64;
;                     f32x4 st[4];
;                     bf16x8 kfr[4][2];
; #pragma unroll
;                     for (int kt = 0; kt < 4; ++kt)
; #pragma unroll
;                         for (int ks = 0; ks < 2; ++ks) kfr[kt][ks] = *(const bf16x8*)(Ks + (kt * 16 + l15) * KROW + ks * 32 + g * 8);
;                     uint2 vfa[8][2], vfb[8][2];
; #pragma unroll
;                     for (int e = 0; e < 8; ++e)
; #pragma unroll
;                         for (int k2 = 0; k2 < 2; ++k2) { const u16* vp = Vt + (e * 16 + l15) * VROW + k2 * 32 + g * 4; vfa[e][k2] = *(const uint2*)vp; vfb[e][k2] = *(const uint2*)(vp + 16); }
;                     __builtin_amdgcn_sched_barrier(0);
; #pragma unroll
;                     for (int kt = 0; kt < 4; ++kt) { st[kt] = (f32x4){0.f, 0.f, 0.f, 0.f};
; #pragma unroll
;                         for (int ks = 0; ks < 2; ++ks) st[kt] = __builtin_amdgcn_mfma_f32_16x16x32_bf16(kfr[kt][ks], qf[ks], st[kt], 0, 0, 0); }
;                     if (kb == qb) {
;                         asm volatile("" ::: "memory");
;                         const int qr = rq * 16 + l15;
; #pragma unroll
;                         for (int kt = 0; kt < 4; ++kt)
; #pragma unroll
;                             for (int jj = 0; jj < 4; ++jj) if (kt * 16 + g * 4 + jj > qr) st[kt][jj] = -INFINITY;
.LBB0_2659:
	ds_read_b128 v[138:141], v208 offset:8192
	ds_read_b128 v[142:145], v209 offset:8192
	ds_read_b128 v[146:149], v208 offset:10240
	ds_read_b128 v[212:215], v209 offset:10240
	ds_read_b128 v[216:219], v208 offset:12288
	ds_read_b128 v[220:223], v209 offset:12288
	ds_read_b128 v[224:227], v208 offset:14336
	ds_read_b128 v[242:245], v209 offset:14336
	ds_read_b128 v[134:137], v205
	ds_read_b128 v[130:133], v204
	ds_read_b128 v[126:129], v205 offset:4096
	ds_read_b128 v[122:125], v204 offset:4096
	ds_read_b128 v[118:121], v205 offset:8192
	ds_read_b128 v[114:117], v204 offset:8192
	ds_read_b128 v[110:113], v205 offset:12288
	ds_read_b128 v[106:109], v204 offset:12288
	ds_read_b128 v[102:105], v205 offset:16384
	ds_read_b128 v[98:101], v204 offset:16384
	ds_read_b128 v[94:97], v205 offset:20480
	ds_read_b128 v[90:93], v204 offset:20480
	ds_read_b128 v[86:89], v205 offset:24576
	ds_read_b128 v[82:85], v204 offset:24576
	ds_read_b128 v[78:81], v205 offset:28672
	ds_read_b128 v[74:77], v204 offset:28672
	s_waitcnt lgkmcnt(14)
	v_mfma_f32_16x16x32_bf16 v[138:141], v[138:141], v[18:21], v[248:251]
	s_cmp_lg_u32 s64, s52
	v_mfma_f32_16x16x32_bf16 v[150:153], v[142:145], v[22:25], v[138:141]
	v_mfma_f32_16x16x32_bf16 v[138:141], v[146:149], v[18:21], v[248:251]
	v_mfma_f32_16x16x32_bf16 v[146:149], v[212:215], v[22:25], v[138:141]
	v_mfma_f32_16x16x32_bf16 v[138:141], v[216:219], v[18:21], v[248:251]
	v_mfma_f32_16x16x32_bf16 v[142:145], v[224:227], v[18:21], v[248:251]
	v_mfma_f32_16x16x32_bf16 v[138:141], v[220:223], v[22:25], v[138:141]
	v_mfma_f32_16x16x32_bf16 v[142:145], v[242:245], v[22:25], v[142:145]
	s_cbranch_scc1 .LBB0_2661
	s_nop 0
	v_cndmask_b32_e64 v173, v150, v241, s[8:9]
	v_cndmask_b32_e64 v150, v173, v150, s[10:11]
	v_cndmask_b32_e64 v151, v241, v151, s[10:11]
	v_cndmask_b32_e64 v152, v152, v241, s[12:13]
	v_cndmask_b32_e64 v153, v153, v241, s[14:15]
	v_cndmask_b32_e64 v146, v146, v241, s[16:17]
	v_cndmask_b32_e64 v147, v147, v241, s[18:19]
	v_cndmask_b32_e64 v148, v148, v241, s[20:21]
	v_cndmask_b32_e64 v149, v149, v241, s[22:23]
	v_cndmask_b32_e64 v138, v138, v241, s[24:25]
	v_cndmask_b32_e64 v139, v139, v241, s[26:27]
	v_cndmask_b32_e64 v140, v140, v241, s[28:29]
	v_cndmask_b32_e64 v141, v141, v241, s[30:31]
	v_cndmask_b32_e64 v142, v142, v241, s[34:35]
	v_cndmask_b32_e64 v143, v143, v241, s[36:37]
	v_cndmask_b32_e64 v144, v144, v241, s[38:39]
	v_cndmask_b32_e64 v145, v145, v241, s[40:41]

; __device__ __forceinline__ unsigned cvt_pk_bf16(float lo, float hi) { unsigned r; asm volatile("s_nop 0\n\tv_cvt_pk_bf16_f32 %0, %1, %2" : "=v"(r) : "v"(lo), "v"(hi)); return r; }
; __device__ __forceinline__ void phase_attn(KP P, int l_, unsigned char* shm) {
;     ...
;                     const float mnew = fmaxf(mrun, mloc), alpha = __builtin_amdgcn_exp2f(mrun - mnew);
;                     mrun = mnew;
;                     float psum = 0.f;
; #pragma unroll
;                     for (int kt = 0; kt < 4; ++kt)
; #pragma unroll
;                         for (int jj = 0; jj < 4; ++jj) { const float p = __builtin_amdgcn_exp2f(st[kt][jj] - mnew); st[kt][jj] = p; psum += p; }
;                     lrun = lrun * alpha + psum;
; #pragma unroll
;                     for (int e = 0; e < 8; ++e) ot[e] *= alpha;
;                     bf16x8 pb[2];
; #pragma unroll
;                     for (int k2 = 0; k2 < 2; ++k2) { uint4 pk; pk.x = cvt_pk_bf16(st[2 * k2][0], st[2 * k2][1]); pk.y = cvt_pk_bf16(st[2 * k2][2], st[2 * k2][3]);
;                         pk.z = cvt_pk_bf16(st[2 * k2 + 1][0], st[2 * k2 + 1][1]); pk.w = cvt_pk_bf16(st[2 * k2 + 1][2], st[2 * k2 + 1][3]);
;                         pb[k2] = as_bf16x8(pk); }
; #pragma unroll
;                     for (int e = 0; e < 8; ++e)
; #pragma unroll
;                         for (int k2 = 0; k2 < 2; ++k2) { const uint2 v0 = vfa[e][k2], v1 = vfb[e][k2];
;                             uint4 vv; vv.x = v0.x; vv.y = v0.y; vv.z = v1.x; vv.w = v1.y;
;                             ot[e] = __builtin_amdgcn_mfma_f32_16x16x32_bf16(as_bf16x8(vv), pb[k2], ot[e], 0, 0, 0); }
;                 }
;             }
;             if (t + 1 < nt) ATT_LSTORE((t + 1) & 1);
;             __syncthreads();
.Lat_comm1:
	v_exp_f32_e32 v150, v150
	v_exp_f32_e32 v151, v151
	v_exp_f32_e32 v152, v152
	v_exp_f32_e32 v153, v153
	v_exp_f32_e32 v146, v146
	v_exp_f32_e32 v147, v147
	v_exp_f32_e32 v148, v148
	v_exp_f32_e32 v149, v149
	v_cvt_pk_bf16_f32 v220, v150, v151
	v_cvt_pk_bf16_f32 v221, v152, v153
	v_cvt_pk_bf16_f32 v222, v146, v147
	v_cvt_pk_bf16_f32 v223, v148, v149
	s_waitcnt lgkmcnt(0)
	s_nop 0
	v_mfma_f32_16x16x32_bf16 v[58:61], v[134:137], v[220:223], v[58:61]
	v_exp_f32_e32 v138, v138
	v_mfma_f32_16x16x32_bf16 v[50:53], v[126:129], v[220:223], v[50:53]
	v_exp_f32_e32 v139, v139
	v_mfma_f32_16x16x32_bf16 v[42:45], v[118:121], v[220:223], v[42:45]
	v_exp_f32_e32 v140, v140
	v_mfma_f32_16x16x32_bf16 v[46:49], v[110:113], v[220:223], v[46:49]
	v_exp_f32_e32 v141, v141
	v_mfma_f32_16x16x32_bf16 v[54:57], v[102:105], v[220:223], v[54:57]
	v_exp_f32_e32 v142, v142
	v_mfma_f32_16x16x32_bf16 v[62:65], v[94:97], v[220:223], v[62:65]
	v_exp_f32_e32 v143, v143
	v_mfma_f32_16x16x32_bf16 v[66:69], v[86:89], v[220:223], v[66:69]
	v_exp_f32_e32 v144, v144
	v_mfma_f32_16x16x32_bf16 v[70:73], v[78:81], v[220:223], v[70:73]
	v_exp_f32_e32 v145, v145
	v_cvt_pk_bf16_f32 v224, v138, v139
	v_cvt_pk_bf16_f32 v225, v140, v141
	v_cvt_pk_bf16_f32 v226, v142, v143
	v_cvt_pk_bf16_f32 v227, v144, v145
	v_add_f32_e32 v187, v150, v151
	v_add_f32_e32 v187, v152, v187
	v_mfma_f32_16x16x32_bf16 v[58:61], v[130:133], v[224:227], v[58:61]
	v_add_f32_e32 v187, v153, v187
	v_add_f32_e32 v187, v146, v187
	v_mfma_f32_16x16x32_bf16 v[50:53], v[122:125], v[224:227], v[50:53]
	v_add_f32_e32 v187, v147, v187
	v_add_f32_e32 v187, v148, v187
	v_mfma_f32_16x16x32_bf16 v[42:45], v[114:117], v[224:227], v[42:45]
	v_add_f32_e32 v187, v149, v187
	v_add_f32_e32 v187, v138, v187
	v_mfma_f32_16x16x32_bf16 v[46:49], v[106:109], v[224:227], v[46:49]
	v_add_f32_e32 v187, v139, v187
	v_add_f32_e32 v187, v140, v187
	v_mfma_f32_16x16x32_bf16 v[54:57], v[98:101], v[224:227], v[54:57]
	v_add_f32_e32 v187, v141, v187
	v_add_f32_e32 v187, v142, v187
	v_mfma_f32_16x16x32_bf16 v[62:65], v[90:93], v[224:227], v[62:65]
	v_add_f32_e32 v187, v143, v187
	v_add_f32_e32 v187, v144, v187
	v_mfma_f32_16x16x32_bf16 v[66:69], v[82:85], v[224:227], v[66:69]
	v_add_f32_e32 v187, v145, v187
	v_mfma_f32_16x16x32_bf16 v[70:73], v[74:77], v[224:227], v[70:73]
	v_add_f32_e32 v171, v171, v187
	s_andn2_b64 vcc, exec, s[56:57]
	s_add_i32 s70, s70, 1
	s_cbranch_vccnz .LBB0_2650
.LBB0_2662:
	s_branch .LBB0_2650
.Lat_rare0:
	v_mov_b32_e32 v187, v186
	s_nop 1
	v_permlane16_swap_b32_e32 v187, v186
	v_max_f32_e32 v186, v186, v187
	v_mov_b32_e32 v187, v186
	s_nop 1
	v_permlane32_swap_b32_e32 v187, v186
	v_max3_f32 v186, v186, v187, v253
	v_sub_f32_e32 v187, 0, v186
	v_min_f32_e32 v187, 0, v187
	v_exp_f32_e32 v246, v187
	v_sub_f32_e32 v150, v150, v186
	v_sub_f32_e32 v151, v151, v186
	v_sub_f32_e32 v152, v152, v186
	v_sub_f32_e32 v153, v153, v186
	v_sub_f32_e32 v146, v146, v186
	v_sub_f32_e32 v147, v147, v186
	v_sub_f32_e32 v148, v148, v186
	v_sub_f32_e32 v149, v149, v186
	v_sub_f32_e32 v138, v138, v186
	v_sub_f32_e32 v139, v139, v186
	v_sub_f32_e32 v140, v140, v186
	v_sub_f32_e32 v141, v141, v186
	v_sub_f32_e32 v142, v142, v186
	v_sub_f32_e32 v143, v143, v186
	v_sub_f32_e32 v144, v144, v186
	v_sub_f32_e32 v145, v145, v186
	v_sub_f32_e32 v248, v248, v186
	v_mov_b32_e32 v252, 0x41000000
	v_mov_b32_e32 v253, 0
	v_mov_b32_e32 v249, v248
	v_mov_b32_e32 v250, v248
	v_mov_b32_e32 v251, v248
	v_mul_f32_e32 v171, v171, v246
	v_pk_mul_f32 v[60:61], v[60:61], v[246:247] op_sel_hi:[1,0]
	v_pk_mul_f32 v[58:59], v[58:59], v[246:247] op_sel_hi:[1,0]
	v_pk_mul_f32 v[52:53], v[52:53], v[246:247] op_sel_hi:[1,0]
	v_pk_mul_f32 v[50:51], v[50:51], v[246:247] op_sel_hi:[1,0]
	v_pk_mul_f32 v[44:45], v[44:45], v[246:247] op_sel_hi:[1,0]
	v_pk_mul_f32 v[42:43], v[42:43], v[246:247] op_sel_hi:[1,0]
	v_pk_mul_f32 v[48:49], v[48:49], v[246:247] op_sel_hi:[1,0]
	v_pk_mul_f32 v[46:47], v[46:47], v[246:247] op_sel_hi:[1,0]
	v_pk_mul_f32 v[56:57], v[56:57], v[246:247] op_sel_hi:[1,0]
	v_pk_mul_f32 v[54:55], v[54:55], v[246:247] op_sel_hi:[1,0]
	v_pk_mul_f32 v[64:65], v[64:65], v[246:247] op_sel_hi:[1,0]
	v_pk_mul_f32 v[62:63], v[62:63], v[246:247] op_sel_hi:[1,0]
	v_pk_mul_f32 v[68:69], v[68:69], v[246:247] op_sel_hi:[1,0]
	v_pk_mul_f32 v[66:67], v[66:67], v[246:247] op_sel_hi:[1,0]
	v_pk_mul_f32 v[72:73], v[72:73], v[246:247] op_sel_hi:[1,0]
	v_pk_mul_f32 v[70:71], v[70:71], v[246:247] op_sel_hi:[1,0]
	s_branch .Lat_comm0

; __global__ void __launch_bounds__(512, 2) mega_fwd(Params Parg) {
;     extern __shared__ __attribute__((aligned(16))) unsigned char shm[];
	.amdhsa_kernel _Z8mega_fwd6Params
		.amdhsa_group_segment_fixed_size 0
		.amdhsa_private_segment_fixed_size 0
		.amdhsa_kernarg_size 512
		.amdhsa_user_sgpr_count 2
		.amdhsa_user_sgpr_dispatch_ptr 0
		.amdhsa_user_sgpr_queue_ptr 0
		.amdhsa_user_sgpr_kernarg_segment_ptr 1
		.amdhsa_user_sgpr_dispatch_id 0
		.amdhsa_user_sgpr_kernarg_preload_length 0
		.amdhsa_user_sgpr_kernarg_preload_offset 0
		.amdhsa_user_sgpr_private_segment_size 0
		.amdhsa_uses_dynamic_stack 0
		.amdhsa_enable_private_segment 0
		.amdhsa_system_sgpr_workgroup_id_x 1
		.amdhsa_system_sgpr_workgroup_id_y 0
		.amdhsa_system_sgpr_workgroup_id_z 0
		.amdhsa_system_sgpr_workgroup_info 0
		.amdhsa_system_vgpr_workitem_id 2
		.amdhsa_next_free_vgpr 256
		.amdhsa_next_free_sgpr 102
		.amdhsa_accum_offset 256
		.amdhsa_reserve_vcc 1
		.amdhsa_float_round_mode_32 0
		.amdhsa_float_round_mode_16_64 0
		.amdhsa_float_denorm_mode_32 3
		.amdhsa_float_denorm_mode_16_64 3
		.amdhsa_dx10_clamp 1
		.amdhsa_ieee_mode 1
		.amdhsa_fp16_overflow 0
		.amdhsa_tg_split 0
		.amdhsa_exception_fp_ieee_invalid_op 0
		.amdhsa_exception_fp_denorm_src 0
		.amdhsa_exception_fp_ieee_div_zero 0
		.amdhsa_exception_fp_ieee_overflow 0
		.amdhsa_exception_fp_ieee_underflow 0
		.amdhsa_exception_fp_ieee_inexact 0
		.amdhsa_exception_int_div_zero 0
	.end_amdhsa_kernel

; __global__ void __launch_bounds__(512, 2) mega_fwd(Params Parg) {
;     extern __shared__ __attribute__((aligned(16))) unsigned char shm[];
amdhsa.kernels:
  - .agpr_count:     0
    .args:
      - .offset:         0
        .size:           256
        .value_kind:     by_value
      - .offset:         256
        .size:           4
        .value_kind:     hidden_block_count_x
      - .offset:         260
        .size:           4
        .value_kind:     hidden_block_count_y
      - .offset:         264
        .size:           4
        .value_kind:     hidden_block_count_z
      - .offset:         268
        .size:           2
        .value_kind:     hidden_group_size_x
      - .offset:         270
        .size:           2
        .value_kind:     hidden_group_size_y
      - .offset:         272
        .size:           2
        .value_kind:     hidden_group_size_z
      - .offset:         274
        .size:           2
        .value_kind:     hidden_remainder_x
      - .offset:         276
        .size:           2
        .value_kind:     hidden_remainder_y
      - .offset:         278
        .size:           2
        .value_kind:     hidden_remainder_z
      - .offset:         296
        .size:           8
        .value_kind:     hidden_global_offset_x
      - .offset:         304
        .size:           8
        .value_kind:     hidden_global_offset_y
      - .offset:         312
        .size:           8
        .value_kind:     hidden_global_offset_z
      - .offset:         320
        .size:           2
        .value_kind:     hidden_grid_dims
      - .offset:         344
        .size:           8
        .value_kind:     hidden_multigrid_sync_arg
      - .offset:         376
        .size:           4
        .value_kind:     hidden_dynamic_lds_size
    .group_segment_fixed_size: 0
    .kernarg_segment_align: 8
    .kernarg_segment_size: 512
    .language:       OpenCL C
    .language_version:
      - 2
      - 0
    .max_flat_workgroup_size: 512
    .name:           _Z8mega_fwd6Params
    .private_segment_fixed_size: 0
    .sgpr_count:     108
    .sgpr_spill_count: 98
    .symbol:         _Z8mega_fwd6Params.kd
    .uniform_work_group_size: 1
    .uses_dynamic_stack: false
    .vgpr_count:     256
    .vgpr_spill_count: 0
    .wavefront_size: 64
